# comb3 + K1: softmax QK^T LDS reads pipelined 3 deep over 4 fragment quads (counted lgkmcnt(2)), no burst
# speedup vs baseline: 1.0003x; 1.0003x over previous
; #define SBAR() __builtin_amdgcn_sched_barrier(0)
; #define A2_LOADT(t) do { const size_t ro_ = (size_t)((t) * 64 + sr) * D + sc; \
;         sk0 = att::load8(c.K + ro_); sk1 = att::load8(c.K + ro_ + 32 * D); sv00 = att::load8(c.V0 + ro_); sv01 = att::load8(c.V0 + ro_ + 32 * D); sv10 = att::load8(c.V1 + ro_); sv11 = att::load8(c.V1 + ro_ + 32 * D); } while (0)
; __device__ __forceinline__ void qkt_rt(f32x16& p0, f32x16& p1, const char* Kb, int r32, int hi, const bf16x8* qr) {
;     p0 = f32x16{}; p1 = f32x16{};
;     const char* kb[4];
; #pragma unroll
;     for (int dd = 0; dd < 4; ++dd) kb[dd] = Kb + KSWZ(r32, (dd * 16 + hi * 8) * 2);
; #pragma unroll
;     for (int d0 = 0; d0 < 8; ++d0) { const char* a = kb[d0 & 3] + (d0 >> 2) * 128;
;         bf16x8 b0 = *reinterpret_cast<const bf16x8*>(a);
;         bf16x8 b1 = *reinterpret_cast<const bf16x8*>(a + 32 * 256);
;         p0 = __builtin_amdgcn_mfma_f32_32x32x16_bf16(b0, qr[d0], p0, 0, 0, 0);
;         p1 = __builtin_amdgcn_mfma_f32_32x32x16_bf16(b1, qr[d0], p1, 0, 0, 0); }
; __device__ __forceinline__ void attn2_block(const Blk& c, char* lds) {
;     ...
;             if (s + 1 < NT) A2_LOADT(s + 1);
;             SBAR();
;             if (s < NT) {
;                 f32x16 p0, p1; float mn, al; bf16x8 pa0, pa1, pa2, pa3;
;                 qkt_rt(p0, p1, lds + L_K + par * SHM_K, r32, hi, qr);
;                 const int kb_ = s * 64;
;                 if (kb_ + 63 > qlo - 128) att::bias_mask_tile(p0, p1, qm - kb_, bt);
.LBB0_552:
	s_and_b32 s88, s30, 1
	s_lshl_b32 s10, s88, 15
	s_add_i32 s10, s10, s100
	s_mov_b32 m0, s10
	v_lshl_add_u64 v[52:53], v[168:169], 0, s[82:83]
	global_load_lds_dwordx4 v[52:53], off
	s_add_i32 m0, s10, 0x380
	v_lshl_add_u64 v[54:55], v[170:171], 0, s[82:83]
	global_load_lds_dwordx4 v[52:53], off offset:128
	s_add_i32 m0, s10, 0x4000
	s_nop 0
	global_load_lds_dwordx4 v[54:55], off
	s_add_i32 m0, s10, 0x4380
	s_nop 0
	global_load_lds_dwordx4 v[54:55], off offset:128
	s_xor_b32 s10, s88, 1
	s_lshl_b32 s10, s10, 14
	s_add_i32 s10, s10, s100
	s_add_i32 m0, s10, 0x10000
	v_lshl_add_u64 v[56:57], v[164:165], 0, s[82:83]
	v_lshl_add_u64 v[58:59], v[166:167], 0, s[82:83]
	global_load_lds_dwordx4 v[56:57], off
	global_load_lds_dwordx4 v[58:59], off offset:1024
	s_lshl_b32 s10, s88, 14
	s_add_i32 s10, s10, 0
	s_add_i32 s10, s10, 0x10000
	v_add3_u32 v40, s10, v121, v119
	ds_read_b128 v[36:39], v40
	ds_read_b128 v[48:51], v40 offset:8192
	v_add3_u32 v41, s10, v122, v119
	ds_read_b128 v[60:63], v41
	v_add3_u32 v42, s10, v123, v119
	v_add3_u32 v43, s10, v124, v119
	v_add3_u32 v44, s10, v126, v119
	v_add3_u32 v45, s10, v127, v119
	v_add3_u32 v46, s10, v128, v119
	v_add3_u32 v47, s10, v129, v119
	s_add_i32 s10, s84, 63
	s_cmp_le_i32 s10, s86
	s_waitcnt lgkmcnt(2)
	v_mfma_f32_32x32x16_bf16 v[20:35], v[36:39], v[104:107], 0
	ds_read_b128 v[64:67], v41 offset:8192
	s_waitcnt lgkmcnt(2)
	v_mfma_f32_32x32x16_bf16 v[4:19], v[48:51], v[104:107], 0
	ds_read_b128 v[36:39], v42
	s_waitcnt lgkmcnt(2)
	v_mfma_f32_32x32x16_bf16 v[20:35], v[60:63], v[100:103], v[20:35]
	ds_read_b128 v[48:51], v42 offset:8192
	s_waitcnt lgkmcnt(2)
	v_mfma_f32_32x32x16_bf16 v[4:19], v[64:67], v[100:103], v[4:19]
	ds_read_b128 v[60:63], v43
	s_waitcnt lgkmcnt(2)
	v_mfma_f32_32x32x16_bf16 v[20:35], v[36:39], v[96:99], v[20:35]
	ds_read_b128 v[64:67], v43 offset:8192
	s_waitcnt lgkmcnt(2)
	v_mfma_f32_32x32x16_bf16 v[4:19], v[48:51], v[96:99], v[4:19]
	ds_read_b128 v[36:39], v44
	s_waitcnt lgkmcnt(2)
	v_mfma_f32_32x32x16_bf16 v[20:35], v[60:63], v[92:95], v[20:35]
	ds_read_b128 v[48:51], v44 offset:8192
	s_waitcnt lgkmcnt(2)
	v_mfma_f32_32x32x16_bf16 v[4:19], v[64:67], v[92:95], v[4:19]
	ds_read_b128 v[60:63], v45
	s_waitcnt lgkmcnt(2)
	v_mfma_f32_32x32x16_bf16 v[20:35], v[36:39], v[88:91], v[20:35]
	ds_read_b128 v[64:67], v45 offset:8192
	s_waitcnt lgkmcnt(2)
	v_mfma_f32_32x32x16_bf16 v[4:19], v[48:51], v[88:91], v[4:19]
	ds_read_b128 v[36:39], v46
	s_waitcnt lgkmcnt(2)
	v_mfma_f32_32x32x16_bf16 v[20:35], v[60:63], v[84:87], v[20:35]
	ds_read_b128 v[48:51], v46 offset:8192
	s_waitcnt lgkmcnt(2)
	v_mfma_f32_32x32x16_bf16 v[4:19], v[64:67], v[84:87], v[4:19]
	ds_read_b128 v[60:63], v47
	s_waitcnt lgkmcnt(2)
	v_mfma_f32_32x32x16_bf16 v[20:35], v[36:39], v[80:83], v[20:35]
	ds_read_b128 v[64:67], v47 offset:8192
	s_waitcnt lgkmcnt(2)
	v_mfma_f32_32x32x16_bf16 v[4:19], v[48:51], v[80:83], v[4:19]
	s_waitcnt lgkmcnt(1)
	v_mfma_f32_32x32x16_bf16 v[20:35], v[60:63], v[76:79], v[20:35]
	s_waitcnt lgkmcnt(0)
	v_mfma_f32_32x32x16_bf16 v[4:19], v[64:67], v[76:79], v[4:19]
	s_cbranch_scc1 .LBB0_586
; __device__ __forceinline__ void bias_mask_tile(f32x16& p0, f32x16& p1, int dq, const float* bt) {
;     const float NEG = -__builtin_inff();
; #pragma unroll
;     for (int r = 0; r < 16; ++r) {
;         const int c = (r & 3) + 8 * (r >> 2);
;         const int d0 = dq - c, d1 = dq - c - 32;
;         const unsigned i0 = (unsigned)d0 < 255u ? (unsigned)d0 : 255u, i1 = (unsigned)d1 < 255u ? (unsigned)d1 : 255u;
;         const float b0 = bt[i0], b1 = bt[i1];
;         p0[r] = d0 >= 0 ? p0[r] + b0 : NEG;
;         p1[r] = d1 >= 0 ? p1[r] + b1 : NEG;
;     }
; }
	v_add_u32_e32 v115, 27, v125
	v_lshl_add_u32 v36, v115, 2, s64
	v_add_u32_e32 v36, 0xffffff14, v36
	ds_read_b32 v132, v36 offset:236
	ds_read_b32 v133, v36 offset:232
	ds_read_b32 v134, v36 offset:228
	ds_read_b32 v135, v36 offset:224
	ds_read_b32 v136, v36 offset:204
	ds_read_b32 v137, v36 offset:200
	ds_read_b32 v138, v36 offset:196
	ds_read_b32 v139, v36 offset:192
	ds_read_b32 v140, v36 offset:172
	ds_read_b32 v141, v36 offset:168
	ds_read_b32 v142, v36 offset:164
	ds_read_b32 v143, v36 offset:160
	ds_read_b32 v144, v36 offset:140
	ds_read_b32 v145, v36 offset:136
	ds_read_b32 v146, v36 offset:132
	v_cmp_lt_i32_e32 vcc, -1, v115
	v_cmp_lt_i32_e64 s[16:17], 0, v115
	s_waitcnt lgkmcnt(14)
	v_add_f32_e32 v20, v20, v132
	ds_read_b32 v147, v36 offset:128
	s_waitcnt lgkmcnt(14)
	v_add_f32_e32 v21, v21, v133
	ds_read_b32 v148, v36 offset:108
	v_cndmask_b32_e32 v20, v240, v20, vcc
	v_cndmask_b32_e64 v21, v240, v21, s[16:17]
	v_cmp_lt_i32_e32 vcc, 1, v115
	v_cmp_lt_i32_e64 s[16:17], 2, v115
	s_waitcnt lgkmcnt(14)
	v_add_f32_e32 v22, v22, v134
	ds_read_b32 v149, v36 offset:104
	s_waitcnt lgkmcnt(14)
	v_add_f32_e32 v23, v23, v135
	ds_read_b32 v150, v36 offset:100
	v_cndmask_b32_e32 v22, v240, v22, vcc
	v_cndmask_b32_e64 v23, v240, v23, s[16:17]
	v_cmp_lt_i32_e32 vcc, 7, v115
	v_cmp_lt_i32_e64 s[16:17], 8, v115
	s_waitcnt lgkmcnt(14)
	v_add_f32_e32 v24, v24, v136
	ds_read_b32 v151, v36 offset:96
	s_waitcnt lgkmcnt(14)
	v_add_f32_e32 v25, v25, v137
	ds_read_b32 v152, v36 offset:76
	v_cndmask_b32_e32 v24, v240, v24, vcc
	v_cndmask_b32_e64 v25, v240, v25, s[16:17]
	v_cmp_lt_i32_e32 vcc, 9, v115
	v_cmp_lt_i32_e64 s[16:17], 10, v115
	s_waitcnt lgkmcnt(14)
	v_add_f32_e32 v26, v26, v138
	ds_read_b32 v153, v36 offset:72
	s_waitcnt lgkmcnt(14)
	v_add_f32_e32 v27, v27, v139
	ds_read_b32 v154, v36 offset:68
	v_cndmask_b32_e32 v26, v240, v26, vcc
	v_cndmask_b32_e64 v27, v240, v27, s[16:17]
	v_cmp_lt_i32_e32 vcc, 15, v115
	v_cmp_lt_i32_e64 s[16:17], 16, v115
	s_waitcnt lgkmcnt(14)
	v_add_f32_e32 v28, v28, v140
	ds_read_b32 v155, v36 offset:64
	s_waitcnt lgkmcnt(14)
	v_add_f32_e32 v29, v29, v141
	ds_read_b32 v60, v36 offset:44
	v_cndmask_b32_e32 v28, v240, v28, vcc
	v_cndmask_b32_e64 v29, v240, v29, s[16:17]
	v_cmp_lt_i32_e32 vcc, 17, v115
	v_cmp_lt_i32_e64 s[16:17], 18, v115
	s_waitcnt lgkmcnt(14)
	v_add_f32_e32 v30, v30, v142
	ds_read_b32 v61, v36 offset:40
	s_waitcnt lgkmcnt(14)
	v_add_f32_e32 v31, v31, v143
	ds_read_b32 v62, v36 offset:36
	v_cndmask_b32_e32 v30, v240, v30, vcc
	v_cndmask_b32_e64 v31, v240, v31, s[16:17]
	v_cmp_lt_i32_e32 vcc, 23, v115
	v_cmp_lt_i32_e64 s[16:17], 24, v115
	s_waitcnt lgkmcnt(14)
	v_add_f32_e32 v32, v32, v144
	ds_read_b32 v63, v36 offset:32
	s_waitcnt lgkmcnt(14)
	v_add_f32_e32 v33, v33, v145
	ds_read_b32 v64, v36 offset:12
	v_cndmask_b32_e32 v32, v240, v32, vcc
	v_cndmask_b32_e64 v33, v240, v33, s[16:17]
	v_cmp_lt_i32_e32 vcc, 25, v115
	v_cmp_lt_i32_e64 s[16:17], 26, v115
	s_waitcnt lgkmcnt(14)
	v_add_f32_e32 v34, v34, v146
	ds_read_b32 v65, v36 offset:8
	s_waitcnt lgkmcnt(14)
	v_add_f32_e32 v35, v35, v147
	ds_read_b32 v66, v36 offset:4
	v_cndmask_b32_e32 v34, v240, v34, vcc
	v_cndmask_b32_e64 v35, v240, v35, s[16:17]
	v_cmp_lt_i32_e32 vcc, 31, v115
	v_cmp_lt_i32_e64 s[16:17], 32, v115
	s_waitcnt lgkmcnt(14)
	v_add_f32_e32 v4, v4, v148
	ds_read_b32 v67, v36 offset:0
	s_waitcnt lgkmcnt(14)
	v_add_f32_e32 v5, v5, v149
	v_cndmask_b32_e32 v4, v240, v4, vcc
	v_cndmask_b32_e64 v5, v240, v5, s[16:17]
	v_cmp_lt_i32_e32 vcc, 33, v115
	v_cmp_lt_i32_e64 s[16:17], 34, v115
	s_waitcnt lgkmcnt(13)
	v_add_f32_e32 v6, v6, v150
	s_waitcnt lgkmcnt(12)
	v_add_f32_e32 v7, v7, v151
	v_cndmask_b32_e32 v6, v240, v6, vcc
	v_cndmask_b32_e64 v7, v240, v7, s[16:17]
	v_cmp_lt_i32_e32 vcc, 39, v115
	v_cmp_lt_i32_e64 s[16:17], 40, v115
	s_waitcnt lgkmcnt(11)
	v_add_f32_e32 v8, v8, v152
	s_waitcnt lgkmcnt(10)
	v_add_f32_e32 v9, v9, v153
	v_cndmask_b32_e32 v8, v240, v8, vcc
	v_cndmask_b32_e64 v9, v240, v9, s[16:17]
	v_cmp_lt_i32_e32 vcc, 41, v115
	v_cmp_lt_i32_e64 s[16:17], 42, v115
	s_waitcnt lgkmcnt(9)
	v_add_f32_e32 v10, v10, v154
	s_waitcnt lgkmcnt(8)
	v_add_f32_e32 v11, v11, v155
	v_cndmask_b32_e32 v10, v240, v10, vcc
	v_cndmask_b32_e64 v11, v240, v11, s[16:17]
	v_cmp_lt_i32_e32 vcc, 47, v115
	v_cmp_lt_i32_e64 s[16:17], 48, v115
	s_waitcnt lgkmcnt(7)
	v_add_f32_e32 v12, v12, v60
	s_waitcnt lgkmcnt(6)
	v_add_f32_e32 v13, v13, v61
	v_cndmask_b32_e32 v12, v240, v12, vcc
	v_cndmask_b32_e64 v13, v240, v13, s[16:17]
	v_cmp_lt_i32_e32 vcc, 49, v115
	v_cmp_lt_i32_e64 s[16:17], 50, v115
	s_waitcnt lgkmcnt(5)
	v_add_f32_e32 v14, v14, v62
	s_waitcnt lgkmcnt(4)
	v_add_f32_e32 v15, v15, v63
	v_cndmask_b32_e32 v14, v240, v14, vcc
	v_cndmask_b32_e64 v15, v240, v15, s[16:17]
	v_cmp_lt_i32_e32 vcc, 55, v115
	v_cmp_lt_i32_e64 s[16:17], 56, v115
	s_waitcnt lgkmcnt(3)
	v_add_f32_e32 v16, v16, v64
	s_waitcnt lgkmcnt(2)
	v_add_f32_e32 v17, v17, v65
	v_cndmask_b32_e32 v16, v240, v16, vcc
	v_cndmask_b32_e64 v17, v240, v17, s[16:17]
	v_cmp_lt_i32_e32 vcc, 57, v115
	v_cmp_lt_i32_e64 s[16:17], 58, v115
	s_waitcnt lgkmcnt(1)
	v_add_f32_e32 v18, v18, v66
	s_waitcnt lgkmcnt(0)
	v_add_f32_e32 v19, v19, v67
	v_cndmask_b32_e32 v18, v240, v18, vcc
	v_cndmask_b32_e64 v19, v240, v19, s[16:17]
